# diff-attention final epilogue de-serialised: the 15 subln gamma loads hoisted and issued together, one counted wait per chunk instead of vmcnt(0) per store
# baseline (speedup 1.0000x reference)
; __global__ void __launch_bounds__(512, 2) mega_fwd(Args a) {
;     ...
;                 float ss = 0.f;
; #pragma unroll
;                 for (int d = 0; d < 4; ++d) {
; #pragma unroll
;                     for (int g4 = 0; g4 < 4; ++g4) { const f32x4 s0 = stash[d * 4 + g4];
; #pragma unroll
;                         for (int j = 0; j < 4; ++j) { const float v = s0[j] - lam * o[d][4 * g4 + j]; o[d][4 * g4 + j] = v; ss += v * v; } }
;                     __builtin_amdgcn_sched_barrier(0); }
;                 ss += __shfl_xor(ss, 32);
;                 const float rinv = rsqrtf(ss * (1.0f / 128.0f) + RMS_EPS) * 0.8f;
;                 bf16_t* op = OA + row * 1024 + h * 128;
; #pragma unroll
;                 for (int d = 0; d < 4; ++d)
; #pragma unroll
;                     for (int g4 = 0; g4 < 4; ++g4) { const int dd = 32 * d + 8 * g4 + 4 * hi; const f32x4 gs = *(const f32x4*)(a.in[10] + dd);
.LBB0_554:
	global_load_dwordx4 v[30:33], v[132:133], off offset:48
	global_load_dwordx4 v[46:49], v[132:133], off offset:32
	global_load_dwordx4 v[78:81], v[132:133], off offset:16
	global_load_dwordx4 v[82:85], v[132:133], off
	global_load_dwordx4 v[86:89], v[132:133], off offset:112
	global_load_dwordx4 v[90:93], v[132:133], off offset:96
	global_load_dwordx4 v[94:97], v[132:133], off offset:80
	global_load_dwordx4 v[98:101], v[132:133], off offset:64
	global_load_dwordx4 v[102:105], v[132:133], off offset:176
	global_load_dwordx4 v[106:109], v[132:133], off offset:160
	global_load_dwordx4 v[110:113], v[132:133], off offset:144
	global_load_dwordx4 v[114:117], v[132:133], off offset:128
	global_load_dwordx4 v[14:17], v[132:133], off offset:240
	global_load_dwordx4 v[118:121], v[132:133], off offset:224
	global_load_dwordx4 v[122:125], v[132:133], off offset:208
	s_nop 0
	global_load_dwordx4 v[132:135], v[132:133], off offset:192
	s_waitcnt vmcnt(3)
	v_pk_fma_f32 v[14:15], v[148:149], v[10:11], v[14:15] neg_lo:[1,0,0] neg_hi:[1,0,0]
	v_pk_fma_f32 v[10:11], v[148:149], v[12:13], v[16:17] neg_lo:[1,0,0] neg_hi:[1,0,0]
	v_pk_mul_f32 v[140:141], v[14:15], v[14:15]
	v_pk_mul_f32 v[142:143], v[10:11], v[10:11]
	v_pk_fma_f32 v[74:75], v[148:149], v[74:75], v[82:83] neg_lo:[1,0,0] neg_hi:[1,0,0]
	v_pk_fma_f32 v[76:77], v[148:149], v[76:77], v[84:85] neg_lo:[1,0,0] neg_hi:[1,0,0]
	v_pk_mul_f32 v[82:83], v[74:75], v[74:75]
	global_load_dwordx4 v[136:139], v126, s[20:21]
	v_pk_mul_f32 v[84:85], v[76:77], v[76:77]
	v_add_f32_e32 v1, v82, v83
	v_pk_fma_f32 v[70:71], v[148:149], v[70:71], v[78:79] neg_lo:[1,0,0] neg_hi:[1,0,0]
	v_add_f32_e32 v1, v1, v84
	v_pk_mul_f32 v[78:79], v[70:71], v[70:71]
	v_add_f32_e32 v1, v1, v85
	v_pk_fma_f32 v[72:73], v[148:149], v[72:73], v[80:81] neg_lo:[1,0,0] neg_hi:[1,0,0]
	v_add_f32_e32 v1, v1, v78
	v_pk_mul_f32 v[80:81], v[72:73], v[72:73]
	v_add_f32_e32 v1, v1, v79
	v_pk_fma_f32 v[66:67], v[148:149], v[66:67], v[46:47] neg_lo:[1,0,0] neg_hi:[1,0,0]
	v_add_f32_e32 v1, v1, v80
	v_pk_mul_f32 v[146:147], v[66:67], v[66:67]
	v_add_f32_e32 v1, v1, v81
	v_pk_fma_f32 v[68:69], v[148:149], v[68:69], v[48:49] neg_lo:[1,0,0] neg_hi:[1,0,0]
	v_add_f32_e32 v1, v1, v146
	v_pk_mul_f32 v[144:145], v[68:69], v[68:69]
	v_add_f32_e32 v1, v1, v147
	v_pk_fma_f32 v[62:63], v[148:149], v[62:63], v[30:31] neg_lo:[1,0,0] neg_hi:[1,0,0]
	v_add_f32_e32 v1, v1, v144
	v_pk_mul_f32 v[152:153], v[62:63], v[62:63]
	v_add_f32_e32 v1, v1, v145
	v_pk_fma_f32 v[64:65], v[148:149], v[64:65], v[32:33] neg_lo:[1,0,0] neg_hi:[1,0,0]
	v_add_f32_e32 v1, v1, v152
	v_pk_mul_f32 v[150:151], v[64:65], v[64:65]
	v_add_f32_e32 v1, v1, v153
	v_pk_fma_f32 v[58:59], v[148:149], v[58:59], v[98:99] neg_lo:[1,0,0] neg_hi:[1,0,0]
	v_add_f32_e32 v1, v1, v150
	v_pk_mul_f32 v[98:99], v[58:59], v[58:59]
	v_add_f32_e32 v1, v1, v151
	v_pk_fma_f32 v[60:61], v[148:149], v[60:61], v[100:101] neg_lo:[1,0,0] neg_hi:[1,0,0]
	v_add_f32_e32 v1, v1, v98
	v_pk_mul_f32 v[100:101], v[60:61], v[60:61]
	v_add_f32_e32 v1, v1, v99
	v_pk_fma_f32 v[54:55], v[148:149], v[54:55], v[94:95] neg_lo:[1,0,0] neg_hi:[1,0,0]
	v_add_f32_e32 v1, v1, v100
	v_pk_mul_f32 v[94:95], v[54:55], v[54:55]
	v_add_f32_e32 v1, v1, v101
	v_pk_fma_f32 v[56:57], v[148:149], v[56:57], v[96:97] neg_lo:[1,0,0] neg_hi:[1,0,0]
	v_add_f32_e32 v1, v1, v94
	v_pk_mul_f32 v[96:97], v[56:57], v[56:57]
	v_add_f32_e32 v1, v1, v95
	v_pk_fma_f32 v[48:49], v[148:149], v[50:51], v[90:91] neg_lo:[1,0,0] neg_hi:[1,0,0]
	v_add_f32_e32 v1, v1, v96
	v_pk_mul_f32 v[50:51], v[48:49], v[48:49]
	v_add_f32_e32 v1, v1, v97
	v_pk_fma_f32 v[46:47], v[148:149], v[52:53], v[92:93] neg_lo:[1,0,0] neg_hi:[1,0,0]
	v_add_f32_e32 v1, v1, v50
	v_pk_mul_f32 v[52:53], v[46:47], v[46:47]
	v_add_f32_e32 v1, v1, v51
	v_pk_fma_f32 v[42:43], v[148:149], v[42:43], v[86:87] neg_lo:[1,0,0] neg_hi:[1,0,0]
	v_add_f32_e32 v1, v1, v52
	v_pk_mul_f32 v[86:87], v[42:43], v[42:43]
	v_add_f32_e32 v1, v1, v53
	v_pk_fma_f32 v[44:45], v[148:149], v[44:45], v[88:89] neg_lo:[1,0,0] neg_hi:[1,0,0]
	v_add_f32_e32 v1, v1, v86
	v_pk_mul_f32 v[88:89], v[44:45], v[44:45]
	v_add_f32_e32 v1, v1, v87
	v_pk_fma_f32 v[38:39], v[148:149], v[38:39], v[114:115] neg_lo:[1,0,0] neg_hi:[1,0,0]
	v_add_f32_e32 v1, v1, v88
	v_pk_mul_f32 v[92:93], v[38:39], v[38:39]
	v_add_f32_e32 v1, v1, v89
	v_pk_fma_f32 v[40:41], v[148:149], v[40:41], v[116:117] neg_lo:[1,0,0] neg_hi:[1,0,0]
	v_add_f32_e32 v1, v1, v92
	v_pk_mul_f32 v[90:91], v[40:41], v[40:41]
	v_add_f32_e32 v1, v1, v93
	v_pk_fma_f32 v[32:33], v[148:149], v[34:35], v[110:111] neg_lo:[1,0,0] neg_hi:[1,0,0]
	v_add_f32_e32 v1, v1, v90
	v_pk_mul_f32 v[34:35], v[32:33], v[32:33]
	v_add_f32_e32 v1, v1, v91
	v_pk_fma_f32 v[30:31], v[148:149], v[36:37], v[112:113] neg_lo:[1,0,0] neg_hi:[1,0,0]
	v_add_f32_e32 v1, v1, v34
	v_pk_mul_f32 v[36:37], v[30:31], v[30:31]
	v_add_f32_e32 v1, v1, v35
	v_pk_fma_f32 v[26:27], v[148:149], v[26:27], v[106:107] neg_lo:[1,0,0] neg_hi:[1,0,0]
	v_add_f32_e32 v1, v1, v36
	v_pk_mul_f32 v[106:107], v[26:27], v[26:27]
	v_add_f32_e32 v1, v1, v37
	v_pk_fma_f32 v[28:29], v[148:149], v[28:29], v[108:109] neg_lo:[1,0,0] neg_hi:[1,0,0]
	v_add_f32_e32 v1, v1, v106
	v_pk_mul_f32 v[108:109], v[28:29], v[28:29]
	v_add_f32_e32 v1, v1, v107
	v_pk_fma_f32 v[22:23], v[148:149], v[22:23], v[102:103] neg_lo:[1,0,0] neg_hi:[1,0,0]
	v_add_f32_e32 v1, v1, v108
	v_pk_mul_f32 v[102:103], v[22:23], v[22:23]
	v_add_f32_e32 v1, v1, v109
	v_pk_fma_f32 v[24:25], v[148:149], v[24:25], v[104:105] neg_lo:[1,0,0] neg_hi:[1,0,0]
	v_add_f32_e32 v1, v1, v102
	v_pk_mul_f32 v[104:105], v[24:25], v[24:25]
	v_add_f32_e32 v1, v1, v103
	s_waitcnt vmcnt(1)
; __device__ __forceinline__ unsigned cvt_pk_bf16(float lo, float hi) { f32x2 v = {lo, hi}; bf16x2_t b = __builtin_convertvector(v, bf16x2_t); return __builtin_bit_cast(unsigned, b); }
; __global__ void __launch_bounds__(512, 2) mega_fwd(Args a) {
;     ...
;                 ss += __shfl_xor(ss, 32);
;                 const float rinv = rsqrtf(ss * (1.0f / 128.0f) + RMS_EPS) * 0.8f;
;                 bf16_t* op = OA + row * 1024 + h * 128;
; #pragma unroll
;                 for (int d = 0; d < 4; ++d)
; #pragma unroll
;                     for (int g4 = 0; g4 < 4; ++g4) { const int dd = 32 * d + 8 * g4 + 4 * hi; const f32x4 gs = *(const f32x4*)(a.in[10] + dd);
;                         u32x2 w; w.x = cvt_pk_bf16(o[d][4 * g4 + 0] * rinv * gs[0], o[d][4 * g4 + 1] * rinv * gs[1]); w.y = cvt_pk_bf16(o[d][4 * g4 + 2] * rinv * gs[2], o[d][4 * g4 + 3] * rinv * gs[3]);
;                         *(u32x2*)(op + dd) = w; }
	v_pk_fma_f32 v[16:17], v[148:149], v[18:19], v[132:133] neg_lo:[1,0,0] neg_hi:[1,0,0]
	v_add_f32_e32 v1, v1, v104
	v_pk_mul_f32 v[18:19], v[16:17], v[16:17]
	v_add_f32_e32 v1, v1, v105
	v_pk_fma_f32 v[12:13], v[148:149], v[20:21], v[134:135] neg_lo:[1,0,0] neg_hi:[1,0,0]
	v_add_f32_e32 v1, v1, v18
	v_pk_mul_f32 v[20:21], v[12:13], v[12:13]
	v_add_f32_e32 v1, v1, v19
	v_pk_fma_f32 v[6:7], v[148:149], v[6:7], v[122:123] neg_lo:[1,0,0] neg_hi:[1,0,0]
	v_add_f32_e32 v1, v1, v20
	v_pk_mul_f32 v[112:113], v[6:7], v[6:7]
	v_add_f32_e32 v1, v1, v21
	v_pk_fma_f32 v[8:9], v[148:149], v[8:9], v[124:125] neg_lo:[1,0,0] neg_hi:[1,0,0]
	v_add_f32_e32 v1, v1, v112
	v_pk_mul_f32 v[110:111], v[8:9], v[8:9]
	v_add_f32_e32 v1, v1, v113
	v_pk_fma_f32 v[2:3], v[148:149], v[2:3], v[118:119] neg_lo:[1,0,0] neg_hi:[1,0,0]
	v_add_f32_e32 v1, v1, v110
	v_pk_mul_f32 v[116:117], v[2:3], v[2:3]
	v_add_f32_e32 v1, v1, v111
	v_pk_fma_f32 v[4:5], v[148:149], v[4:5], v[120:121] neg_lo:[1,0,0] neg_hi:[1,0,0]
	v_add_f32_e32 v1, v1, v116
	v_pk_mul_f32 v[114:115], v[4:5], v[4:5]
	v_add_f32_e32 v1, v1, v117
	v_add_f32_e32 v1, v1, v114
	v_add_f32_e32 v1, v1, v115
	v_add_f32_e32 v1, v1, v140
	v_add_f32_e32 v1, v1, v141
	v_add_f32_e32 v1, v1, v142
	v_add_f32_e32 v1, v1, v143
	global_load_dwordx4 v[78:81], v126, s[20:21] offset:32
	global_load_dwordx4 v[82:85], v126, s[20:21] offset:64
	global_load_dwordx4 v[86:89], v126, s[20:21] offset:96
	global_load_dwordx4 v[90:93], v126, s[20:21] offset:128
	global_load_dwordx4 v[94:97], v126, s[20:21] offset:160
	global_load_dwordx4 v[98:101], v126, s[20:21] offset:192
	global_load_dwordx4 v[102:105], v126, s[20:21] offset:224
	global_load_dwordx4 v[106:109], v126, s[20:21] offset:256
	global_load_dwordx4 v[110:113], v126, s[20:21] offset:288
	global_load_dwordx4 v[114:117], v126, s[20:21] offset:320
	global_load_dwordx4 v[118:121], v126, s[20:21] offset:352
	global_load_dwordx4 v[122:125], v126, s[20:21] offset:384
	global_load_dwordx4 v[140:143], v126, s[20:21] offset:416
	global_load_dwordx4 v[144:147], v126, s[20:21] offset:448
	global_load_dwordx4 v[150:153], v126, s[20:21] offset:480
	ds_bpermute_b32 v20, v223, v1
	s_mov_b32 s0, 0x800000
	v_lshlrev_b64 v[18:19], 11, v[128:129]
	v_lshl_add_u64 v[18:19], s[38:39], 0, v[18:19]
	s_lshl_b32 s10, s14, 1
	s_waitcnt lgkmcnt(0)
	v_add_f32_e32 v1, v1, v20
	v_fmamk_f32 v1, v1, 0x3c000000, v210
	v_mul_f32_e32 v20, 0x4b800000, v1
	v_cmp_gt_f32_e32 vcc, s0, v1
	v_lshl_add_u64 v[18:19], v[18:19], 0, s[10:11]
	v_mov_b32_e32 v131, v0
	v_cndmask_b32_e32 v1, v1, v20, vcc
	v_rsq_f32_e32 v1, v1
	v_lshl_add_u64 v[18:19], v[18:19], 0, v[130:131]
	v_mul_f32_e32 v20, 0x45800000, v1
	v_cndmask_b32_e32 v1, v1, v20, vcc
	v_mul_f32_e32 v20, 0x3f4ccccd, v1
	s_waitcnt vmcnt(15)
	v_pk_mul_f32 v[74:75], v[20:21], v[74:75] op_sel_hi:[0,1]
	v_pk_mul_f32 v[76:77], v[20:21], v[76:77] op_sel_hi:[0,1]
	v_pk_mul_f32 v[136:137], v[136:137], v[74:75]
	v_pk_mul_f32 v[138:139], v[138:139], v[76:77]
	v_cvt_pk_bf16_f32 v136, v136, v137
	v_cvt_pk_bf16_f32 v137, v138, v139
	global_store_dwordx2 v[18:19], v[136:137], off
	s_waitcnt vmcnt(15)
	v_pk_mul_f32 v[70:71], v[20:21], v[70:71] op_sel_hi:[0,1]
	v_pk_mul_f32 v[72:73], v[20:21], v[72:73] op_sel_hi:[0,1]
	v_pk_mul_f32 v[78:79], v[78:79], v[70:71]
	v_pk_mul_f32 v[80:81], v[80:81], v[72:73]
	v_cvt_pk_bf16_f32 v78, v78, v79
	v_cvt_pk_bf16_f32 v79, v80, v81
	global_store_dwordx2 v[18:19], v[78:79], off offset:16
	s_waitcnt vmcnt(15)
	v_pk_mul_f32 v[66:67], v[20:21], v[66:67] op_sel_hi:[0,1]
	v_pk_mul_f32 v[68:69], v[20:21], v[68:69] op_sel_hi:[0,1]
	v_pk_mul_f32 v[82:83], v[82:83], v[66:67]
	v_pk_mul_f32 v[84:85], v[84:85], v[68:69]
	v_cvt_pk_bf16_f32 v82, v82, v83
	v_cvt_pk_bf16_f32 v83, v84, v85
	global_store_dwordx2 v[18:19], v[82:83], off offset:32
	s_waitcnt vmcnt(15)
	v_pk_mul_f32 v[62:63], v[20:21], v[62:63] op_sel_hi:[0,1]
	v_pk_mul_f32 v[64:65], v[20:21], v[64:65] op_sel_hi:[0,1]
	v_pk_mul_f32 v[86:87], v[86:87], v[62:63]
	v_pk_mul_f32 v[88:89], v[88:89], v[64:65]
	v_cvt_pk_bf16_f32 v86, v86, v87
	v_cvt_pk_bf16_f32 v87, v88, v89
	global_store_dwordx2 v[18:19], v[86:87], off offset:48
	s_waitcnt vmcnt(15)
; __device__ __forceinline__ unsigned cvt_pk_bf16(float lo, float hi) { f32x2 v = {lo, hi}; bf16x2_t b = __builtin_convertvector(v, bf16x2_t); return __builtin_bit_cast(unsigned, b); }
; __global__ void __launch_bounds__(512, 2) mega_fwd(Args a) {
;     ...
;                 bf16_t* op = OA + row * 1024 + h * 128;
; #pragma unroll
;                 for (int d = 0; d < 4; ++d)
; #pragma unroll
;                     for (int g4 = 0; g4 < 4; ++g4) { const int dd = 32 * d + 8 * g4 + 4 * hi; const f32x4 gs = *(const f32x4*)(a.in[10] + dd);
;                         u32x2 w; w.x = cvt_pk_bf16(o[d][4 * g4 + 0] * rinv * gs[0], o[d][4 * g4 + 1] * rinv * gs[1]); w.y = cvt_pk_bf16(o[d][4 * g4 + 2] * rinv * gs[2], o[d][4 * g4 + 3] * rinv * gs[3]);
;                         *(u32x2*)(op + dd) = w; }
	v_pk_mul_f32 v[58:59], v[20:21], v[58:59] op_sel_hi:[0,1]
	v_pk_mul_f32 v[60:61], v[20:21], v[60:61] op_sel_hi:[0,1]
	v_pk_mul_f32 v[90:91], v[90:91], v[58:59]
	v_pk_mul_f32 v[92:93], v[92:93], v[60:61]
	v_cvt_pk_bf16_f32 v90, v90, v91
	v_cvt_pk_bf16_f32 v91, v92, v93
	global_store_dwordx2 v[18:19], v[90:91], off offset:64
	s_waitcnt vmcnt(15)
	v_pk_mul_f32 v[54:55], v[20:21], v[54:55] op_sel_hi:[0,1]
	v_pk_mul_f32 v[56:57], v[20:21], v[56:57] op_sel_hi:[0,1]
	v_pk_mul_f32 v[94:95], v[94:95], v[54:55]
	v_pk_mul_f32 v[96:97], v[96:97], v[56:57]
	v_cvt_pk_bf16_f32 v94, v94, v95
	v_cvt_pk_bf16_f32 v95, v96, v97
	global_store_dwordx2 v[18:19], v[94:95], off offset:80
	s_waitcnt vmcnt(15)
	v_pk_mul_f32 v[48:49], v[20:21], v[48:49] op_sel_hi:[0,1]
	v_pk_mul_f32 v[46:47], v[20:21], v[46:47] op_sel_hi:[0,1]
	v_pk_mul_f32 v[98:99], v[98:99], v[48:49]
	v_pk_mul_f32 v[100:101], v[100:101], v[46:47]
	v_cvt_pk_bf16_f32 v98, v98, v99
	v_cvt_pk_bf16_f32 v99, v100, v101
	global_store_dwordx2 v[18:19], v[98:99], off offset:96
	s_waitcnt vmcnt(15)
	v_pk_mul_f32 v[42:43], v[20:21], v[42:43] op_sel_hi:[0,1]
	v_pk_mul_f32 v[44:45], v[20:21], v[44:45] op_sel_hi:[0,1]
	v_pk_mul_f32 v[102:103], v[102:103], v[42:43]
	v_pk_mul_f32 v[104:105], v[104:105], v[44:45]
	v_cvt_pk_bf16_f32 v102, v102, v103
	v_cvt_pk_bf16_f32 v103, v104, v105
	global_store_dwordx2 v[18:19], v[102:103], off offset:112
	s_waitcnt vmcnt(15)
	v_pk_mul_f32 v[38:39], v[20:21], v[38:39] op_sel_hi:[0,1]
	v_pk_mul_f32 v[40:41], v[20:21], v[40:41] op_sel_hi:[0,1]
	v_pk_mul_f32 v[106:107], v[106:107], v[38:39]
	v_pk_mul_f32 v[108:109], v[108:109], v[40:41]
	v_cvt_pk_bf16_f32 v106, v106, v107
	v_cvt_pk_bf16_f32 v107, v108, v109
	global_store_dwordx2 v[18:19], v[106:107], off offset:128
	s_waitcnt vmcnt(15)
	v_pk_mul_f32 v[32:33], v[20:21], v[32:33] op_sel_hi:[0,1]
	v_pk_mul_f32 v[30:31], v[20:21], v[30:31] op_sel_hi:[0,1]
	v_pk_mul_f32 v[110:111], v[110:111], v[32:33]
	v_pk_mul_f32 v[112:113], v[112:113], v[30:31]
	v_cvt_pk_bf16_f32 v110, v110, v111
	v_cvt_pk_bf16_f32 v111, v112, v113
	global_store_dwordx2 v[18:19], v[110:111], off offset:144
	s_waitcnt vmcnt(15)
	v_pk_mul_f32 v[26:27], v[20:21], v[26:27] op_sel_hi:[0,1]
	v_pk_mul_f32 v[28:29], v[20:21], v[28:29] op_sel_hi:[0,1]
	v_pk_mul_f32 v[114:115], v[114:115], v[26:27]
	v_pk_mul_f32 v[116:117], v[116:117], v[28:29]
	v_cvt_pk_bf16_f32 v114, v114, v115
	v_cvt_pk_bf16_f32 v115, v116, v117
	global_store_dwordx2 v[18:19], v[114:115], off offset:160
	s_waitcnt vmcnt(15)
	v_pk_mul_f32 v[22:23], v[20:21], v[22:23] op_sel_hi:[0,1]
	v_pk_mul_f32 v[24:25], v[20:21], v[24:25] op_sel_hi:[0,1]
	v_pk_mul_f32 v[118:119], v[118:119], v[22:23]
	v_pk_mul_f32 v[120:121], v[120:121], v[24:25]
	v_cvt_pk_bf16_f32 v118, v118, v119
	v_cvt_pk_bf16_f32 v119, v120, v121
	global_store_dwordx2 v[18:19], v[118:119], off offset:176
	s_waitcnt vmcnt(15)
	v_pk_mul_f32 v[16:17], v[20:21], v[16:17] op_sel_hi:[0,1]
	v_pk_mul_f32 v[12:13], v[20:21], v[12:13] op_sel_hi:[0,1]
	v_pk_mul_f32 v[122:123], v[122:123], v[16:17]
	v_pk_mul_f32 v[124:125], v[124:125], v[12:13]
	v_cvt_pk_bf16_f32 v122, v122, v123
	v_cvt_pk_bf16_f32 v123, v124, v125
	global_store_dwordx2 v[18:19], v[122:123], off offset:192
	s_waitcnt vmcnt(15)
	v_pk_mul_f32 v[6:7], v[20:21], v[6:7] op_sel_hi:[0,1]
	v_pk_mul_f32 v[8:9], v[20:21], v[8:9] op_sel_hi:[0,1]
	v_pk_mul_f32 v[140:141], v[140:141], v[6:7]
	v_pk_mul_f32 v[142:143], v[142:143], v[8:9]
	v_cvt_pk_bf16_f32 v140, v140, v141
	v_cvt_pk_bf16_f32 v141, v142, v143
	global_store_dwordx2 v[18:19], v[140:141], off offset:208
	s_waitcnt vmcnt(15)
	v_pk_mul_f32 v[2:3], v[20:21], v[2:3] op_sel_hi:[0,1]
	v_pk_mul_f32 v[4:5], v[20:21], v[4:5] op_sel_hi:[0,1]
	v_pk_mul_f32 v[144:145], v[144:145], v[2:3]
	v_pk_mul_f32 v[146:147], v[146:147], v[4:5]
	v_cvt_pk_bf16_f32 v144, v144, v145
	v_cvt_pk_bf16_f32 v145, v146, v147
	global_store_dwordx2 v[18:19], v[144:145], off offset:224
	s_waitcnt vmcnt(15)
	v_pk_mul_f32 v[14:15], v[20:21], v[14:15] op_sel_hi:[0,1]
	v_pk_mul_f32 v[10:11], v[20:21], v[10:11] op_sel_hi:[0,1]
	v_pk_mul_f32 v[150:151], v[150:151], v[14:15]
	v_pk_mul_f32 v[152:153], v[152:153], v[10:11]
	v_cvt_pk_bf16_f32 v150, v150, v151
	v_cvt_pk_bf16_f32 v151, v152, v153
	global_store_dwordx2 v[18:19], v[150:151], off offset:240
